# P6: first four half row-groups of the residual fetched in the phase prologue into v224..v255 (free during the K-loop); the epilogue's first four serial load rounds use them
# speedup vs baseline: 1.0051x; 1.0051x over previous
; #define PG8_STAGE(bufoff, gbase, voff) do { _Pragma("unroll") for (int _i = 0; _i < 2; ++_i) \
;         __builtin_amdgcn_global_load_lds((const unsigned*)((const char*)(gbase) + (voff)[_i]), (PG8_LAS unsigned*)(lds + (bufoff) + ldsw + _i * 8192), 16, 0, 0); } while (0)
; #define PG8_WAIT_V(n) asm volatile("s_waitcnt vmcnt(" #n ")" ::: "memory")
; #define PG8_BAR __builtin_amdgcn_s_barrier()
;     __device__ __forceinline__ void operator()(PG8_ACC, const Unit& u, int wr, int wc, int fr, int fq) const {
;     ...
;             for (int m = 0; m < 4; ++m) { const size_t off = (size_t)(row0 + ai * HALF + m * 16) * ld + col0;
; #pragma unroll
;                 for (int bj = 0; bj < 2; ++bj) {
;                     const f32x4 r0 = *(const f32x4*)(res + off + bj * HALF), r1 = *(const f32x4*)(res + off + bj * HALF + 4);
; template <class Epi, class Sched, bool ALIGN_EPI = false, bool SP2 = false>
; __device__ __forceinline__ void gemm_phase(PG8_LAS unsigned char* lds, const Gemm g, const Sched& S, const Epi& E, int wave_id) {
;     ...
;         PG8_STAGE(PG8_SB(0, 0), cB, voffB); PG8_STAGE(PG8_SB(0, 1), cB + hstepB, voffB); PG8_STAGE(PG8_SA(0, 0), cA, voffA); PG8_STAGE(PG8_SA(0, 1), cA + hstepA, voffA);
;         if (wr == 1) PG8_BAR;
;         PG8_WAIT_V(2); PG8_BAR;
;         PG8_STAGE(PG8_SB(1, 0), cB + kstep, voffB); PG8_STAGE(PG8_SA(1, 0), cA + kstep, voffA); PG8_STAGE(PG8_SB(1, 1), cB + hstepB + kstep, voffB);
;         PG8_WAIT_V(6); PG8_BAR;
.LBB0_791:
	s_lshl_b32 s1, s1, 5
	s_mov_b64 s[16:17], 0x80
	s_and_b32 s1, s1, 0x60
	s_add_i32 m0, s33, 0x18000
	v_lshl_add_u64 v[6:7], v[6:7], 0, s[16:17]
	s_lshl_b32 s19, s5, 13
	s_lshl_b32 s22, s1, 7
	s_waitcnt vmcnt(2)
	s_barrier
	global_load_lds_dwordx4 v[6:7], off
	v_lshl_add_u64 v[4:5], v[4:5], 0, s[16:17]
	s_add_i32 m0, s33, 0x1a000
	s_add_i32 s44, s33, 0x8000
	s_add_i32 s45, s33, 0xa000
	global_load_lds_dwordx4 v[4:5], off
	v_lshl_add_u64 v[0:1], v[0:1], 0, s[16:17]
	s_mov_b32 m0, s44
	s_add_u32 s20, s34, 0xb0080
	global_load_lds_dwordx4 v[0:1], off
	v_lshl_add_u64 v[0:1], v[2:3], 0, s[16:17]
	s_mov_b32 m0, s45
	s_addc_u32 s21, s35, 0
	global_load_lds_dwordx4 v[0:1], off
	s_add_i32 m0, s33, 0x1c000
	v_lshl_add_u64 v[0:1], s[20:21], 0, v[130:131]
	global_load_lds_dwordx4 v[0:1], off
	v_lshl_add_u64 v[0:1], s[20:21], 0, v[134:135]
	s_add_i32 m0, s33, 0x1e000
	s_mov_b32 s20, 0x1a000
	global_load_lds_dwordx4 v[0:1], off
	v_lshrrev_b32_e32 v1, 1, v8
	v_and_b32_e32 v1, 24, v1
	v_and_b32_e32 v0, 15, v8
	v_lshlrev_b32_e32 v2, 1, v1
	v_lshl_or_b32 v150, s5, 6, v0
	v_lshl_or_b32 v0, v0, 6, v2
	v_lshlrev_b32_e32 v2, 2, v8
	v_and_b32_e32 v2, 32, v2
	v_bitop3_b32 v3, v0, s19, v2 bitop3:0xde
	v_bitop3_b32 v151, v0, s22, v2 bitop3:0xde
	v_or_b32_e32 v152, s1, v1
	v_lshrrev_b32_e32 v1, 1, v9
	v_mul_lo_u32 v0, v10, s0
	s_cmpk_lt_u32 s4, 0x100
	v_mad_u64_u32 v[0:1], s[4:5], v1, s20, v[0:1]
	v_or_b32_e32 v0, v0, v11
	v_add_lshl_u32 v0, v0, v12, 1
	v_mov_b32_e32 v1, v131
	s_mov_b64 s[4:5], 0x1a0080
	v_lshl_add_u64 v[136:137], v[0:1], 0, s[4:5]
	v_lshrrev_b32_e32 v1, 1, v13
	v_mul_lo_u32 v0, v14, s0
	v_mad_u64_u32 v[0:1], s[0:1], v1, s20, v[0:1]
	s_waitcnt vmcnt(6)
	v_or_b32_e32 v0, v0, v15
	s_sext_i32_i8 s55, s18
	s_cselect_b64 s[18:19], -1, 0
	v_add_lshl_u32 v0, v0, v16, 1
	v_mov_b32_e32 v1, v131
	s_add_i32 s46, 0, 0x10000
	s_add_i32 s47, 0, 0x14000
	v_lshl_add_u64 v[138:139], v[0:1], 0, s[4:5]
	v_mov_b64_e32 v[140:141], 0x100
	v_mov_b64_e32 v[142:143], 0xff
	v_add_u32_e32 v153, s46, v151
	v_add_u32_e32 v154, s47, v151
	v_add_u32_e32 v155, 0, v3
	s_mov_b64 s[20:21], 0x80000
	s_mov_b32 s48, 0x80000
	s_mov_b64 s[22:23], 0x90000
	s_mov_b32 s49, 0x90000
	s_mov_b64 s[26:27], 0xa0000
	s_mov_b32 s50, 0xa0000
	s_mov_b32 s51, 0xb0000
	v_lshl_add_u32 v248, s54, 8, v150
	v_lshl_or_b32 v250, s55, 8, v152
	v_ashrrev_i32_e32 v249, 31, v248
	v_ashrrev_i32_e32 v251, 31, v250
	v_lshlrev_b64 v[248:249], 12, v[248:249]
	v_lshl_add_u64 v[248:249], s[12:13], 0, v[248:249]
	v_lshlrev_b64 v[250:251], 2, v[250:251]
	v_lshl_add_u64 v[248:249], v[248:249], 0, v[250:251]
	s_mov_b64 s[100:101], 0x10000
	global_load_dwordx4 v[224:227], v[248:249], off offset:16
	global_load_dwordx4 v[228:231], v[248:249], off
	global_load_dwordx4 v[232:235], v[248:249], off offset:528
	global_load_dwordx4 v[236:239], v[248:249], off offset:512
	v_lshl_add_u64 v[250:251], v[248:249], 0, s[100:101]
	global_load_dwordx4 v[240:243], v[250:251], off offset:16
	global_load_dwordx4 v[244:247], v[250:251], off
	global_load_dwordx4 v[252:255], v[250:251], off offset:528
	global_load_dwordx4 v[248:251], v[250:251], off offset:512
	s_barrier
	s_branch .LBB0_794

;     __device__ __forceinline__ void operator()(PG8_ACC, const Unit& u, int wr, int wc, int fr, int fq) const {
;     ...
; #pragma unroll
;         for (int ai = 0; ai < 2; ++ai)
; #pragma unroll
;             for (int m = 0; m < 4; ++m) { const size_t off = (size_t)(row0 + ai * HALF + m * 16) * ld + col0;
; #pragma unroll
;                 for (int bj = 0; bj < 2; ++bj) {
;                     const f32x4 r0 = *(const f32x4*)(res + off + bj * HALF), r1 = *(const f32x4*)(res + off + bj * HALF + 4);
;                     const f32x4 v0 = acc[ai][bj][m][0] + r0, v1 = acc[ai][bj][m][1] + r1;
;                     *(f32x4*)(out + off + bj * HALF) = v0; *(f32x4*)(out + off + bj * HALF + 4) = v1; } }
.LBB0_808:
	v_lshl_add_u32 v146, s54, 8, v150
	v_lshl_or_b32 v144, s55, 8, v152
	v_ashrrev_i32_e32 v147, 31, v146
	v_ashrrev_i32_e32 v145, 31, v144
	v_lshlrev_b64 v[148:149], 12, v[146:147]
	v_lshl_add_u64 v[156:157], s[12:13], 0, v[148:149]
	v_lshlrev_b64 v[148:149], 2, v[144:145]
	v_lshl_add_u64 v[144:145], v[156:157], 0, v[148:149]
	s_mov_b64 s[30:31], -1
	s_waitcnt vmcnt(0)
	v_pk_add_f32 v[122:123], v[122:123], v[226:227]
	v_pk_add_f32 v[126:127], v[126:127], v[230:231]
	v_pk_add_f32 v[124:125], v[124:125], v[228:229]
	v_pk_add_f32 v[120:121], v[120:121], v[224:225]
	global_store_dwordx4 v[144:145], v[124:127], off
	global_store_dwordx4 v[144:145], v[120:123], off offset:16
	v_pk_add_f32 v[112:113], v[112:113], v[232:233]
	v_pk_add_f32 v[118:119], v[118:119], v[238:239]
	v_pk_add_f32 v[116:117], v[116:117], v[236:237]
	v_pk_add_f32 v[114:115], v[114:115], v[234:235]
	global_store_dwordx4 v[144:145], v[116:119], off offset:512
	global_store_dwordx4 v[144:145], v[112:115], off offset:528
	s_nop 1
	v_or_b32_e32 v112, 16, v146
	v_ashrrev_i32_e32 v113, 31, v112
	v_lshlrev_b64 v[112:113], 12, v[112:113]
	v_lshl_add_u64 v[112:113], s[12:13], 0, v[112:113]
	v_lshl_add_u64 v[120:121], v[112:113], 0, v[148:149]
	v_pk_add_f32 v[106:107], v[106:107], v[242:243]
	v_pk_add_f32 v[110:111], v[110:111], v[246:247]
	v_pk_add_f32 v[108:109], v[108:109], v[244:245]
	v_pk_add_f32 v[104:105], v[104:105], v[240:241]
	global_store_dwordx4 v[120:121], v[108:111], off
	global_store_dwordx4 v[120:121], v[104:107], off offset:16
	v_pk_add_f32 v[96:97], v[96:97], v[252:253]
	v_pk_add_f32 v[102:103], v[102:103], v[250:251]
	v_pk_add_f32 v[100:101], v[100:101], v[248:249]
	v_pk_add_f32 v[98:99], v[98:99], v[254:255]
	global_store_dwordx4 v[120:121], v[100:103], off offset:512
	global_store_dwordx4 v[120:121], v[96:99], off offset:528
	s_nop 1
	v_or_b32_e32 v96, 32, v146
	v_ashrrev_i32_e32 v97, 31, v96
	v_lshlrev_b64 v[96:97], 12, v[96:97]
	v_lshl_add_u64 v[96:97], s[12:13], 0, v[96:97]
	v_lshl_add_u64 v[104:105], v[96:97], 0, v[148:149]
	global_load_dwordx4 v[96:99], v[104:105], off offset:16
	global_load_dwordx4 v[100:103], v[104:105], off
	s_waitcnt vmcnt(1)
	v_pk_add_f32 v[90:91], v[90:91], v[98:99]
	s_waitcnt vmcnt(0)
	v_pk_add_f32 v[94:95], v[94:95], v[102:103]
	v_pk_add_f32 v[92:93], v[92:93], v[100:101]
	v_pk_add_f32 v[88:89], v[88:89], v[96:97]
	global_store_dwordx4 v[104:105], v[92:95], off
	global_store_dwordx4 v[104:105], v[88:91], off offset:16
	global_load_dwordx4 v[88:91], v[104:105], off offset:528
	s_nop 0
	global_load_dwordx4 v[92:95], v[104:105], off offset:512
	s_waitcnt vmcnt(1)
	v_pk_add_f32 v[80:81], v[80:81], v[88:89]
	s_waitcnt vmcnt(0)
	v_pk_add_f32 v[86:87], v[86:87], v[94:95]
	v_pk_add_f32 v[84:85], v[84:85], v[92:93]
	v_pk_add_f32 v[82:83], v[82:83], v[90:91]
	global_store_dwordx4 v[104:105], v[84:87], off offset:512
	global_store_dwordx4 v[104:105], v[80:83], off offset:528
	s_nop 1
	v_or_b32_e32 v80, 48, v146
	v_ashrrev_i32_e32 v81, 31, v80
	v_lshlrev_b64 v[80:81], 12, v[80:81]
	v_lshl_add_u64 v[80:81], s[12:13], 0, v[80:81]
	v_lshl_add_u64 v[88:89], v[80:81], 0, v[148:149]
	global_load_dwordx4 v[80:83], v[88:89], off offset:16
	global_load_dwordx4 v[84:87], v[88:89], off
	s_waitcnt vmcnt(1)
	v_pk_add_f32 v[74:75], v[74:75], v[82:83]
	s_waitcnt vmcnt(0)
	v_pk_add_f32 v[78:79], v[78:79], v[86:87]
	v_pk_add_f32 v[76:77], v[76:77], v[84:85]
	v_pk_add_f32 v[72:73], v[72:73], v[80:81]
	global_store_dwordx4 v[88:89], v[76:79], off
	global_store_dwordx4 v[88:89], v[72:75], off offset:16
	global_load_dwordx4 v[72:75], v[88:89], off offset:528
	s_nop 0
	global_load_dwordx4 v[76:79], v[88:89], off offset:512
	s_waitcnt vmcnt(1)
	v_pk_add_f32 v[66:67], v[66:67], v[74:75]
	s_waitcnt vmcnt(0)
	v_pk_add_f32 v[70:71], v[70:71], v[78:79]
	v_pk_add_f32 v[68:69], v[68:69], v[76:77]
	v_add_co_u32_e32 v74, vcc, s48, v144
	v_pk_add_f32 v[64:65], v[64:65], v[72:73]
	global_store_dwordx4 v[88:89], v[68:71], off offset:512
	global_store_dwordx4 v[88:89], v[64:67], off offset:528
	v_addc_co_u32_e32 v75, vcc, 0, v145, vcc
	v_lshl_add_u64 v[72:73], v[144:145], 0, s[20:21]
	global_load_dwordx4 v[64:67], v[74:75], off
	global_load_dwordx4 v[68:71], v[72:73], off offset:16
	s_waitcnt vmcnt(1)
;     __device__ __forceinline__ void operator()(PG8_ACC, const Unit& u, int wr, int wc, int fr, int fq) const {
;     ...
; #pragma unroll
;         for (int ai = 0; ai < 2; ++ai)
; #pragma unroll
;             for (int m = 0; m < 4; ++m) { const size_t off = (size_t)(row0 + ai * HALF + m * 16) * ld + col0;
; #pragma unroll
;                 for (int bj = 0; bj < 2; ++bj) {
;                     const f32x4 r0 = *(const f32x4*)(res + off + bj * HALF), r1 = *(const f32x4*)(res + off + bj * HALF + 4);
;                     const f32x4 v0 = acc[ai][bj][m][0] + r0, v1 = acc[ai][bj][m][1] + r1;
;                     *(f32x4*)(out + off + bj * HALF) = v0; *(f32x4*)(out + off + bj * HALF + 4) = v1; } }
	v_pk_add_f32 v[62:63], v[62:63], v[66:67]
	v_pk_add_f32 v[60:61], v[60:61], v[64:65]
	s_waitcnt vmcnt(0)
	v_pk_add_f32 v[58:59], v[58:59], v[70:71]
	v_pk_add_f32 v[56:57], v[56:57], v[68:69]
	global_store_dwordx4 v[74:75], v[60:63], off
	global_store_dwordx4 v[72:73], v[56:59], off offset:16
	global_load_dwordx4 v[56:59], v[72:73], off offset:528
	s_nop 0
	global_load_dwordx4 v[60:63], v[72:73], off offset:512
	s_waitcnt vmcnt(1)
	v_pk_add_f32 v[50:51], v[50:51], v[58:59]
	s_waitcnt vmcnt(0)
	v_pk_add_f32 v[54:55], v[54:55], v[62:63]
	v_pk_add_f32 v[52:53], v[52:53], v[60:61]
	v_add_co_u32_e32 v58, vcc, s49, v144
	v_pk_add_f32 v[48:49], v[48:49], v[56:57]
	global_store_dwordx4 v[72:73], v[52:55], off offset:512
	global_store_dwordx4 v[72:73], v[48:51], off offset:528
	v_addc_co_u32_e32 v59, vcc, 0, v145, vcc
	v_lshl_add_u64 v[56:57], v[144:145], 0, s[22:23]
	global_load_dwordx4 v[48:51], v[58:59], off
	global_load_dwordx4 v[52:55], v[56:57], off offset:16
	s_waitcnt vmcnt(1)
	v_pk_add_f32 v[46:47], v[46:47], v[50:51]
	v_pk_add_f32 v[44:45], v[44:45], v[48:49]
	s_waitcnt vmcnt(0)
	v_pk_add_f32 v[42:43], v[42:43], v[54:55]
	v_pk_add_f32 v[40:41], v[40:41], v[52:53]
	global_store_dwordx4 v[58:59], v[44:47], off
	global_store_dwordx4 v[56:57], v[40:43], off offset:16
	global_load_dwordx4 v[40:43], v[56:57], off offset:528
	s_nop 0
	global_load_dwordx4 v[44:47], v[56:57], off offset:512
	s_waitcnt vmcnt(1)
	v_pk_add_f32 v[34:35], v[34:35], v[42:43]
	s_waitcnt vmcnt(0)
	v_pk_add_f32 v[38:39], v[38:39], v[46:47]
	v_pk_add_f32 v[36:37], v[36:37], v[44:45]
	v_add_co_u32_e32 v42, vcc, s50, v144
	v_pk_add_f32 v[32:33], v[32:33], v[40:41]
	global_store_dwordx4 v[56:57], v[36:39], off offset:512
	global_store_dwordx4 v[56:57], v[32:35], off offset:528
	v_addc_co_u32_e32 v43, vcc, 0, v145, vcc
	v_lshl_add_u64 v[40:41], v[144:145], 0, s[26:27]
	global_load_dwordx4 v[32:35], v[42:43], off
	global_load_dwordx4 v[36:39], v[40:41], off offset:16
	s_waitcnt vmcnt(1)
	v_pk_add_f32 v[30:31], v[30:31], v[34:35]
	v_pk_add_f32 v[28:29], v[28:29], v[32:33]
	s_waitcnt vmcnt(0)
	v_pk_add_f32 v[26:27], v[26:27], v[38:39]
	v_pk_add_f32 v[24:25], v[24:25], v[36:37]
	global_store_dwordx4 v[42:43], v[28:31], off
	global_store_dwordx4 v[40:41], v[24:27], off offset:16
	global_load_dwordx4 v[24:27], v[40:41], off offset:528
	s_nop 0
	global_load_dwordx4 v[28:31], v[40:41], off offset:512
	s_waitcnt vmcnt(1)
	v_pk_add_f32 v[18:19], v[18:19], v[26:27]
	s_waitcnt vmcnt(0)
	v_pk_add_f32 v[22:23], v[22:23], v[30:31]
	v_pk_add_f32 v[20:21], v[20:21], v[28:29]
	v_add_co_u32_e32 v26, vcc, s51, v144
	v_pk_add_f32 v[16:17], v[16:17], v[24:25]
	global_store_dwordx4 v[40:41], v[20:23], off offset:512
	global_store_dwordx4 v[40:41], v[16:19], off offset:528
	v_addc_co_u32_e32 v27, vcc, 0, v145, vcc
	s_nop 0
	v_lshl_add_u64 v[16:17], v[144:145], 0, s[10:11]
	global_load_dwordx4 v[18:21], v[26:27], off
	global_load_dwordx4 v[22:25], v[16:17], off offset:16
	s_and_b64 vcc, exec, s[0:1]
	s_waitcnt vmcnt(1)
	v_pk_add_f32 v[14:15], v[14:15], v[20:21]
	v_pk_add_f32 v[12:13], v[12:13], v[18:19]
	s_waitcnt vmcnt(0)
	v_pk_add_f32 v[10:11], v[10:11], v[24:25]
	v_pk_add_f32 v[8:9], v[8:9], v[22:23]
	global_store_dwordx4 v[26:27], v[12:15], off
	global_store_dwordx4 v[16:17], v[8:11], off offset:16
	global_load_dwordx4 v[8:11], v[16:17], off offset:528
	s_nop 0
	global_load_dwordx4 v[12:15], v[16:17], off offset:512
	s_waitcnt vmcnt(1)
	v_pk_add_f32 v[2:3], v[2:3], v[10:11]
	s_waitcnt vmcnt(0)
	v_pk_add_f32 v[6:7], v[6:7], v[14:15]
	v_pk_add_f32 v[4:5], v[4:5], v[12:13]
	v_pk_add_f32 v[0:1], v[0:1], v[8:9]
	global_store_dwordx4 v[16:17], v[4:7], off offset:512
	global_store_dwordx4 v[16:17], v[0:3], off offset:528
	s_cbranch_vccnz .LBB0_793
	s_andn2_b64 vcc, exec, s[14:15]
	s_cbranch_vccnz .LBB0_792
	s_barrier
	s_branch .LBB0_792
